# EpiResid epilogues: wait only for own residual loads (vmcnt(12)) instead of draining the next tile's prologue loads
# speedup vs baseline: 1.0903x; 1.0021x over previous
; #define TIDX get_tid_()
; DI int crow(int i, int h) { return (i & 3) + 8 * (i >> 2) + 4 * h; }
;   DI void operator()(const f32x16 (&acc)[2][2], int m0, int n0, const float (&rv)[2][2][16]) const {
;     const int tid = TIDX, lane = tid & 63, wid = tid >> 6, wr = wid >> 1, wc = wid & 1, r = lane & 31, h = lane >> 5;
; #pragma unroll
;     for (int mi = 0; mi < 2; ++mi)
; #pragma unroll
;       for (int ni = 0; ni < 2; ++ni)
; #pragma unroll
;         for (int i = 0; i < 16; ++i)
;           out[(size_t)(m0 + wr * 64 + mi * 32 + crow(i, h)) * DM + n0 + wc * 64 + ni * 32 + r] = rv[mi][ni][i] + scale * acc[mi][ni][i];
;   }
.LBB0_30:
	v_mov_b32_e32 v64, v129
	s_waitcnt vmcnt(12)
	v_fmac_f32_e32 v155, 0.5, v48
	v_ashrrev_i32_e32 v66, 1, v64
	v_and_b32_e32 v66, 0xffffffc0, v66
	v_and_b32_e32 v65, 64, v64
	v_and_b32_e32 v68, 31, v64
	v_lshrrev_b32_e32 v64, 3, v64
	v_add_u32_e32 v66, s10, v66
	v_and_or_b32 v64, v64, 4, v66
	v_lshlrev_b32_e32 v130, 2, v65
	v_or_b32_e32 v48, 1, v64
	v_fmac_f32_e32 v153, 0.5, v50
	v_or_b32_e32 v70, 2, v64
	v_or_b32_e32 v50, 3, v64
	v_fmac_f32_e32 v152, 0.5, v52
	v_or_b32_e32 v72, 8, v64
	v_or_b32_e32 v52, 9, v64
	v_fmac_f32_e32 v148, 0.5, v54
	v_or_b32_e32 v74, 10, v64
	v_or_b32_e32 v54, 11, v64
	v_fmac_f32_e32 v145, 0.5, v56
	v_or_b32_e32 v76, 16, v64
	v_or_b32_e32 v56, 17, v64
	v_fmac_f32_e32 v140, 0.5, v58
	v_or_b32_e32 v78, 18, v64
	v_or_b32_e32 v58, 19, v64
	v_fmac_f32_e32 v137, 0.5, v60
	v_or_b32_e32 v80, 24, v64
	v_or_b32_e32 v60, 25, v64
	v_fmac_f32_e32 v132, 0.5, v62
	v_or_b32_e32 v82, 26, v64
	v_or_b32_e32 v62, 27, v64
	v_fmac_f32_e32 v120, 0.5, v32
	v_fmac_f32_e32 v111, 0.5, v34
	v_fmac_f32_e32 v119, 0.5, v36
	v_fmac_f32_e32 v110, 0.5, v38
	v_fmac_f32_e32 v118, 0.5, v40
	v_fmac_f32_e32 v109, 0.5, v42
	v_fmac_f32_e32 v117, 0.5, v44
	v_fmac_f32_e32 v108, 0.5, v46
	v_or_b32_e32 v32, 32, v64
	v_fmac_f32_e32 v149, 0.5, v16
	v_or_b32_e32 v16, 33, v64
	v_fmac_f32_e32 v144, 0.5, v18
	v_or_b32_e32 v34, 34, v64
	v_or_b32_e32 v18, 35, v64
	v_fmac_f32_e32 v142, 0.5, v20
	v_or_b32_e32 v36, 40, v64
	v_or_b32_e32 v20, 41, v64
	v_fmac_f32_e32 v136, 0.5, v22
	v_or_b32_e32 v38, 42, v64
	v_or_b32_e32 v22, 43, v64
	v_fmac_f32_e32 v133, 0.5, v24
	v_or_b32_e32 v40, 48, v64
	v_or_b32_e32 v24, 49, v64
	v_fmac_f32_e32 v125, 0.5, v26
	v_or_b32_e32 v42, 50, v64
	v_or_b32_e32 v26, 51, v64
	v_fmac_f32_e32 v123, 0.5, v28
	v_or_b32_e32 v44, 56, v64
	v_or_b32_e32 v28, 57, v64
	v_fmac_f32_e32 v121, 0.5, v30
	v_or_b32_e32 v46, 58, v64
	v_or_b32_e32 v30, 59, v64
	v_lshl_add_u64 v[66:67], s[8:9], 0, v[130:131]
	v_lshlrev_b32_e32 v130, 2, v68
	v_ashrrev_i32_e32 v65, 31, v64
	v_fmac_f32_e32 v154, 0.5, v49
	v_ashrrev_i32_e32 v49, 31, v48
	v_ashrrev_i32_e32 v71, 31, v70
	v_fmac_f32_e32 v151, 0.5, v51
	v_ashrrev_i32_e32 v51, 31, v50
	v_ashrrev_i32_e32 v73, 31, v72
	v_fmac_f32_e32 v150, 0.5, v53
	v_ashrrev_i32_e32 v53, 31, v52
	v_ashrrev_i32_e32 v75, 31, v74
	v_fmac_f32_e32 v146, 0.5, v55
	v_ashrrev_i32_e32 v55, 31, v54
	v_ashrrev_i32_e32 v77, 31, v76
	v_fmac_f32_e32 v143, 0.5, v57
	v_ashrrev_i32_e32 v57, 31, v56
	v_ashrrev_i32_e32 v79, 31, v78
	v_fmac_f32_e32 v138, 0.5, v59
	v_ashrrev_i32_e32 v59, 31, v58
	v_ashrrev_i32_e32 v81, 31, v80
	v_fmac_f32_e32 v135, 0.5, v61
	v_ashrrev_i32_e32 v61, 31, v60
	v_ashrrev_i32_e32 v83, 31, v82
	v_fmac_f32_e32 v126, 0.5, v63
	v_ashrrev_i32_e32 v63, 31, v62
	v_fmac_f32_e32 v116, 0.5, v33
	v_fmac_f32_e32 v107, 0.5, v35
	v_fmac_f32_e32 v115, 0.5, v37
	v_fmac_f32_e32 v106, 0.5, v39
	v_fmac_f32_e32 v114, 0.5, v41
	v_fmac_f32_e32 v105, 0.5, v43
	v_fmac_f32_e32 v112, 0.5, v45
	v_fmac_f32_e32 v104, 0.5, v47
	v_ashrrev_i32_e32 v33, 31, v32
	v_fmac_f32_e32 v147, 0.5, v17
	v_ashrrev_i32_e32 v17, 31, v16
	v_ashrrev_i32_e32 v35, 31, v34
	v_fmac_f32_e32 v141, 0.5, v19
	v_ashrrev_i32_e32 v19, 31, v18
	v_ashrrev_i32_e32 v37, 31, v36
	v_fmac_f32_e32 v139, 0.5, v21
	v_ashrrev_i32_e32 v21, 31, v20
	v_ashrrev_i32_e32 v39, 31, v38
	v_fmac_f32_e32 v134, 0.5, v23
	v_ashrrev_i32_e32 v23, 31, v22
	v_ashrrev_i32_e32 v41, 31, v40
	v_fmac_f32_e32 v127, 0.5, v25
	v_ashrrev_i32_e32 v25, 31, v24
	v_ashrrev_i32_e32 v43, 31, v42
	v_fmac_f32_e32 v124, 0.5, v27
	v_ashrrev_i32_e32 v27, 31, v26
	v_ashrrev_i32_e32 v45, 31, v44
	v_fmac_f32_e32 v122, 0.5, v29
	v_ashrrev_i32_e32 v29, 31, v28
	v_ashrrev_i32_e32 v47, 31, v46
	v_fmac_f32_e32 v113, 0.5, v31
	v_ashrrev_i32_e32 v31, 31, v30
	v_lshl_add_u64 v[66:67], v[66:67], 0, v[130:131]
	v_lshlrev_b64 v[68:69], 12, v[64:65]
	v_lshlrev_b64 v[48:49], 12, v[48:49]
	v_lshlrev_b64 v[70:71], 12, v[70:71]
	v_lshlrev_b64 v[50:51], 12, v[50:51]
	v_lshlrev_b64 v[72:73], 12, v[72:73]
	v_lshlrev_b64 v[52:53], 12, v[52:53]
	v_lshlrev_b64 v[74:75], 12, v[74:75]
	v_lshlrev_b64 v[54:55], 12, v[54:55]
	v_lshlrev_b64 v[76:77], 12, v[76:77]
	v_lshlrev_b64 v[56:57], 12, v[56:57]
	v_lshlrev_b64 v[78:79], 12, v[78:79]
	v_lshlrev_b64 v[58:59], 12, v[58:59]
	v_lshlrev_b64 v[80:81], 12, v[80:81]
	v_lshlrev_b64 v[60:61], 12, v[60:61]
	v_lshlrev_b64 v[82:83], 12, v[82:83]
	v_lshlrev_b64 v[62:63], 12, v[62:63]
	v_lshlrev_b64 v[32:33], 12, v[32:33]
	v_lshlrev_b64 v[16:17], 12, v[16:17]
	v_lshlrev_b64 v[34:35], 12, v[34:35]
	v_lshlrev_b64 v[18:19], 12, v[18:19]
	v_lshlrev_b64 v[36:37], 12, v[36:37]
	v_lshlrev_b64 v[20:21], 12, v[20:21]
	v_lshlrev_b64 v[38:39], 12, v[38:39]
	v_lshlrev_b64 v[22:23], 12, v[22:23]
	v_lshlrev_b64 v[40:41], 12, v[40:41]
	v_lshlrev_b64 v[24:25], 12, v[24:25]
	v_lshlrev_b64 v[42:43], 12, v[42:43]
	v_lshlrev_b64 v[26:27], 12, v[26:27]
	v_lshlrev_b64 v[44:45], 12, v[44:45]
	v_lshlrev_b64 v[28:29], 12, v[28:29]
	v_lshlrev_b64 v[46:47], 12, v[46:47]
	v_lshlrev_b64 v[30:31], 12, v[30:31]
; #define TIDX get_tid_()
; DI int crow(int i, int h) { return (i & 3) + 8 * (i >> 2) + 4 * h; }
;   DI void operator()(const f32x16 (&acc)[2][2], int m0, int n0, const float (&rv)[2][2][16]) const {
;     const int tid = TIDX, lane = tid & 63, wid = tid >> 6, wr = wid >> 1, wc = wid & 1, r = lane & 31, h = lane >> 5;
; #pragma unroll
;     for (int mi = 0; mi < 2; ++mi)
; #pragma unroll
;       for (int ni = 0; ni < 2; ++ni)
; #pragma unroll
;         for (int i = 0; i < 16; ++i)
;           out[(size_t)(m0 + wr * 64 + mi * 32 + crow(i, h)) * DM + n0 + wc * 64 + ni * 32 + r] = rv[mi][ni][i] + scale * acc[mi][ni][i];
;   }
	v_lshl_add_u64 v[68:69], v[66:67], 0, v[68:69]
	v_lshl_add_u64 v[48:49], v[66:67], 0, v[48:49]
	v_lshl_add_u64 v[70:71], v[66:67], 0, v[70:71]
	v_lshl_add_u64 v[50:51], v[66:67], 0, v[50:51]
	v_lshl_add_u64 v[72:73], v[66:67], 0, v[72:73]
	v_lshl_add_u64 v[52:53], v[66:67], 0, v[52:53]
	v_lshl_add_u64 v[74:75], v[66:67], 0, v[74:75]
	v_lshl_add_u64 v[54:55], v[66:67], 0, v[54:55]
	v_lshl_add_u64 v[76:77], v[66:67], 0, v[76:77]
	v_lshl_add_u64 v[56:57], v[66:67], 0, v[56:57]
	v_lshl_add_u64 v[78:79], v[66:67], 0, v[78:79]
	v_lshl_add_u64 v[58:59], v[66:67], 0, v[58:59]
	v_lshl_add_u64 v[80:81], v[66:67], 0, v[80:81]
	v_lshl_add_u64 v[60:61], v[66:67], 0, v[60:61]
	v_lshl_add_u64 v[82:83], v[66:67], 0, v[82:83]
	v_lshl_add_u64 v[62:63], v[66:67], 0, v[62:63]
	v_lshl_add_u64 v[32:33], v[66:67], 0, v[32:33]
	v_lshl_add_u64 v[16:17], v[66:67], 0, v[16:17]
	v_lshl_add_u64 v[34:35], v[66:67], 0, v[34:35]
	v_lshl_add_u64 v[18:19], v[66:67], 0, v[18:19]
	v_lshl_add_u64 v[36:37], v[66:67], 0, v[36:37]
	v_lshl_add_u64 v[20:21], v[66:67], 0, v[20:21]
	v_lshl_add_u64 v[38:39], v[66:67], 0, v[38:39]
	v_lshl_add_u64 v[22:23], v[66:67], 0, v[22:23]
	v_lshl_add_u64 v[40:41], v[66:67], 0, v[40:41]
	v_lshl_add_u64 v[24:25], v[66:67], 0, v[24:25]
	v_lshl_add_u64 v[42:43], v[66:67], 0, v[42:43]
	v_lshl_add_u64 v[26:27], v[66:67], 0, v[26:27]
	v_lshl_add_u64 v[44:45], v[66:67], 0, v[44:45]
	v_lshl_add_u64 v[28:29], v[66:67], 0, v[28:29]
	v_lshl_add_u64 v[46:47], v[66:67], 0, v[46:47]
	v_lshl_add_u64 v[30:31], v[66:67], 0, v[30:31]
	v_fmac_f32_e32 v103, 0.5, v0
	v_fmac_f32_e32 v99, 0.5, v1
	v_fmac_f32_e32 v95, 0.5, v2
	v_fmac_f32_e32 v91, 0.5, v3
	v_fmac_f32_e32 v102, 0.5, v4
	v_fmac_f32_e32 v98, 0.5, v5
	v_fmac_f32_e32 v94, 0.5, v6
	v_fmac_f32_e32 v90, 0.5, v7
	v_fmac_f32_e32 v101, 0.5, v8
	v_fmac_f32_e32 v97, 0.5, v9
	v_fmac_f32_e32 v93, 0.5, v10
	v_fmac_f32_e32 v89, 0.5, v11
	v_fmac_f32_e32 v100, 0.5, v12
	v_fmac_f32_e32 v96, 0.5, v13
	v_fmac_f32_e32 v92, 0.5, v14
	v_fmac_f32_e32 v88, 0.5, v15
	s_and_b64 vcc, exec, s[14:15]
	global_store_dword v[68:69], v155, off
	global_store_dword v[48:49], v154, off
	global_store_dword v[70:71], v153, off
	global_store_dword v[50:51], v151, off
	global_store_dword v[72:73], v152, off
	global_store_dword v[52:53], v150, off
	global_store_dword v[74:75], v148, off
	global_store_dword v[54:55], v146, off
	global_store_dword v[76:77], v145, off
	global_store_dword v[56:57], v143, off
	global_store_dword v[78:79], v140, off
	global_store_dword v[58:59], v138, off
	global_store_dword v[80:81], v137, off
	global_store_dword v[60:61], v135, off
	global_store_dword v[82:83], v132, off
	global_store_dword v[62:63], v126, off
	global_store_dword v[68:69], v120, off offset:128
	global_store_dword v[48:49], v116, off offset:128
	global_store_dword v[70:71], v111, off offset:128
	global_store_dword v[50:51], v107, off offset:128
	global_store_dword v[72:73], v119, off offset:128
	global_store_dword v[52:53], v115, off offset:128
	global_store_dword v[74:75], v110, off offset:128
	global_store_dword v[54:55], v106, off offset:128
	global_store_dword v[76:77], v118, off offset:128
	global_store_dword v[56:57], v114, off offset:128
	global_store_dword v[78:79], v109, off offset:128
	global_store_dword v[58:59], v105, off offset:128
	global_store_dword v[80:81], v117, off offset:128
	global_store_dword v[60:61], v112, off offset:128
	global_store_dword v[82:83], v108, off offset:128
	global_store_dword v[62:63], v104, off offset:128
	global_store_dword v[32:33], v149, off
	global_store_dword v[16:17], v147, off
	global_store_dword v[34:35], v144, off
	global_store_dword v[18:19], v141, off
	global_store_dword v[36:37], v142, off
	global_store_dword v[20:21], v139, off
	global_store_dword v[38:39], v136, off
	global_store_dword v[22:23], v134, off
	global_store_dword v[40:41], v133, off
	global_store_dword v[24:25], v127, off
	global_store_dword v[42:43], v125, off
	global_store_dword v[26:27], v124, off
	global_store_dword v[44:45], v123, off
	global_store_dword v[28:29], v122, off
	global_store_dword v[46:47], v121, off
	global_store_dword v[30:31], v113, off
	global_store_dword v[32:33], v103, off offset:128
	global_store_dword v[16:17], v99, off offset:128
	global_store_dword v[34:35], v95, off offset:128
	global_store_dword v[18:19], v91, off offset:128
	global_store_dword v[36:37], v102, off offset:128
	global_store_dword v[20:21], v98, off offset:128
	global_store_dword v[38:39], v94, off offset:128
	global_store_dword v[22:23], v90, off offset:128
	global_store_dword v[40:41], v101, off offset:128
	global_store_dword v[24:25], v97, off offset:128
	global_store_dword v[42:43], v93, off offset:128
	global_store_dword v[26:27], v89, off offset:128
	global_store_dword v[44:45], v100, off offset:128
	global_store_dword v[28:29], v96, off offset:128
	global_store_dword v[46:47], v92, off offset:128
	global_store_dword v[30:31], v88, off offset:128
	s_cbranch_vccnz .LBB0_44

; #define TIDX get_tid_()
; DI int crow(int i, int h) { return (i & 3) + 8 * (i >> 2) + 4 * h; }
;   DI void operator()(const f32x16 (&acc)[2][2], int m0, int n0, const float (&rv)[2][2][16]) const {
;     const int tid = TIDX, lane = tid & 63, wid = tid >> 6, wr = wid >> 1, wc = wid & 1, r = lane & 31, h = lane >> 5;
; #pragma unroll
;     for (int mi = 0; mi < 2; ++mi)
; #pragma unroll
;       for (int ni = 0; ni < 2; ++ni)
; #pragma unroll
;         for (int i = 0; i < 16; ++i)
;           out[(size_t)(m0 + wr * 64 + mi * 32 + crow(i, h)) * DM + n0 + wc * 64 + ni * 32 + r] = rv[mi][ni][i] + scale * acc[mi][ni][i];
;   }
.LBB0_83:
	v_mov_b32_e32 v64, v129
	s_waitcnt vmcnt(12)
	v_add_f32_e32 v48, v143, v48
	v_ashrrev_i32_e32 v66, 1, v64
	v_and_b32_e32 v66, 0xffffffc0, v66
	v_and_b32_e32 v65, 64, v64
	v_and_b32_e32 v68, 31, v64
	v_lshrrev_b32_e32 v64, 3, v64
	v_add_u32_e32 v66, s26, v66
	v_and_or_b32 v64, v64, 4, v66
	v_lshlrev_b32_e32 v130, 2, v65
	v_lshl_add_u64 v[66:67], s[68:69], 0, v[130:131]
	v_lshlrev_b32_e32 v130, 2, v68
	v_ashrrev_i32_e32 v65, 31, v64
	v_lshl_add_u64 v[66:67], v[66:67], 0, v[130:131]
	v_lshlrev_b64 v[68:69], 12, v[64:65]
	v_lshl_add_u64 v[68:69], v[66:67], 0, v[68:69]
	v_or_b32_e32 v70, 2, v64
	global_store_dword v[68:69], v48, off
	v_or_b32_e32 v48, 1, v64
	v_ashrrev_i32_e32 v71, 31, v70
	v_add_f32_e32 v65, v141, v49
	v_ashrrev_i32_e32 v49, 31, v48
	v_lshlrev_b64 v[70:71], 12, v[70:71]
	v_lshlrev_b64 v[48:49], 12, v[48:49]
	v_add_f32_e32 v50, v139, v50
	v_lshl_add_u64 v[70:71], v[66:67], 0, v[70:71]
	v_or_b32_e32 v72, 8, v64
	v_lshl_add_u64 v[48:49], v[66:67], 0, v[48:49]
	global_store_dword v[70:71], v50, off
	v_or_b32_e32 v50, 3, v64
	v_ashrrev_i32_e32 v73, 31, v72
	global_store_dword v[48:49], v65, off
	v_add_f32_e32 v65, v136, v51
	v_ashrrev_i32_e32 v51, 31, v50
	v_lshlrev_b64 v[72:73], 12, v[72:73]
	v_lshlrev_b64 v[50:51], 12, v[50:51]
	v_add_f32_e32 v52, v137, v52
	v_lshl_add_u64 v[72:73], v[66:67], 0, v[72:73]
	v_lshl_add_u64 v[50:51], v[66:67], 0, v[50:51]
	global_store_dword v[72:73], v52, off
	v_or_b32_e32 v52, 9, v64
	global_store_dword v[50:51], v65, off
	v_add_f32_e32 v65, v133, v53
	v_ashrrev_i32_e32 v53, 31, v52
	v_or_b32_e32 v74, 10, v64
	v_lshlrev_b64 v[52:53], 12, v[52:53]
	v_ashrrev_i32_e32 v75, 31, v74
	v_lshl_add_u64 v[52:53], v[66:67], 0, v[52:53]
	v_lshlrev_b64 v[74:75], 12, v[74:75]
	global_store_dword v[52:53], v65, off
	v_add_f32_e32 v54, v127, v54
	v_lshl_add_u64 v[74:75], v[66:67], 0, v[74:75]
	v_add_f32_e32 v65, v124, v55
	v_or_b32_e32 v124, 16, v64
	global_store_dword v[74:75], v54, off
	v_or_b32_e32 v54, 11, v64
	v_add_f32_e32 v56, v125, v56
	v_ashrrev_i32_e32 v125, 31, v124
	v_ashrrev_i32_e32 v55, 31, v54
	v_lshlrev_b64 v[124:125], 12, v[124:125]
	v_lshlrev_b64 v[54:55], 12, v[54:55]
	v_lshl_add_u64 v[124:125], v[66:67], 0, v[124:125]
	v_add_f32_e32 v32, v95, v32
	v_lshl_add_u64 v[54:55], v[66:67], 0, v[54:55]
	global_store_dword v[124:125], v56, off
	v_or_b32_e32 v56, 17, v64
	global_store_dword v[68:69], v32, off offset:128
	v_add_f32_e32 v32, v89, v33
	global_store_dword v[54:55], v65, off
	v_add_f32_e32 v65, v121, v57
	v_ashrrev_i32_e32 v57, 31, v56
	v_or_b32_e32 v136, 18, v64
	global_store_dword v[48:49], v32, off offset:128
	v_add_f32_e32 v32, v83, v34
	v_lshlrev_b64 v[56:57], 12, v[56:57]
	v_ashrrev_i32_e32 v137, 31, v136
	global_store_dword v[70:71], v32, off offset:128
	v_add_f32_e32 v32, v79, v35
	v_lshl_add_u64 v[56:57], v[66:67], 0, v[56:57]
	v_lshlrev_b64 v[136:137], 12, v[136:137]
	global_store_dword v[50:51], v32, off offset:128
	v_add_f32_e32 v32, v101, v36
	global_store_dword v[56:57], v65, off
	v_add_f32_e32 v58, v119, v58
	v_lshl_add_u64 v[136:137], v[66:67], 0, v[136:137]
	v_add_f32_e32 v65, v116, v59
	v_or_b32_e32 v116, 24, v64
	global_store_dword v[72:73], v32, off offset:128
	v_add_f32_e32 v32, v96, v37
	global_store_dword v[136:137], v58, off
	v_or_b32_e32 v58, 19, v64
	v_add_f32_e32 v60, v117, v60
	v_ashrrev_i32_e32 v117, 31, v116
	global_store_dword v[52:53], v32, off offset:128
	v_add_f32_e32 v32, v90, v38
	v_ashrrev_i32_e32 v59, 31, v58
	v_lshlrev_b64 v[116:117], 12, v[116:117]
	global_store_dword v[74:75], v32, off offset:128
	v_add_f32_e32 v32, v84, v39
	v_lshlrev_b64 v[58:59], 12, v[58:59]
	v_lshl_add_u64 v[116:117], v[66:67], 0, v[116:117]
	v_or_b32_e32 v144, 26, v64
	global_store_dword v[54:55], v32, off offset:128
	v_add_f32_e32 v32, v105, v40
	v_lshl_add_u64 v[58:59], v[66:67], 0, v[58:59]
	global_store_dword v[116:117], v60, off
	v_or_b32_e32 v60, 25, v64
	v_ashrrev_i32_e32 v145, 31, v144
	global_store_dword v[124:125], v32, off offset:128
	v_add_f32_e32 v32, v102, v41
	global_store_dword v[58:59], v65, off
	v_add_f32_e32 v65, v113, v61
	v_ashrrev_i32_e32 v61, 31, v60
	v_lshlrev_b64 v[144:145], 12, v[144:145]
	global_store_dword v[56:57], v32, off offset:128
	v_add_f32_e32 v32, v97, v42
	v_lshlrev_b64 v[60:61], 12, v[60:61]
	v_add_f32_e32 v62, v111, v62
	v_lshl_add_u64 v[144:145], v[66:67], 0, v[144:145]
	global_store_dword v[136:137], v32, off offset:128
	v_add_f32_e32 v32, v91, v43
	v_lshl_add_u64 v[60:61], v[66:67], 0, v[60:61]
	global_store_dword v[144:145], v62, off
	v_or_b32_e32 v62, 27, v64
	global_store_dword v[58:59], v32, off offset:128
	v_add_f32_e32 v32, v107, v44
	global_store_dword v[60:61], v65, off
	v_add_f32_e32 v65, v109, v63
	v_ashrrev_i32_e32 v63, 31, v62
	global_store_dword v[116:117], v32, off offset:128
	v_add_f32_e32 v32, v106, v45
	v_lshlrev_b64 v[62:63], 12, v[62:63]
	global_store_dword v[60:61], v32, off offset:128
	v_add_f32_e32 v32, v103, v46
; #define TIDX get_tid_()
; DI int crow(int i, int h) { return (i & 3) + 8 * (i >> 2) + 4 * h; }
;   DI void operator()(const f32x16 (&acc)[2][2], int m0, int n0, const float (&rv)[2][2][16]) const {
;     const int tid = TIDX, lane = tid & 63, wid = tid >> 6, wr = wid >> 1, wc = wid & 1, r = lane & 31, h = lane >> 5;
; #pragma unroll
;     for (int mi = 0; mi < 2; ++mi)
; #pragma unroll
;       for (int ni = 0; ni < 2; ++ni)
; #pragma unroll
;         for (int i = 0; i < 16; ++i)
;           out[(size_t)(m0 + wr * 64 + mi * 32 + crow(i, h)) * DM + n0 + wc * 64 + ni * 32 + r] = rv[mi][ni][i] + scale * acc[mi][ni][i];
;   }
	v_lshl_add_u64 v[62:63], v[66:67], 0, v[62:63]
	global_store_dword v[144:145], v32, off offset:128
	v_add_f32_e32 v32, v98, v47
	global_store_dword v[62:63], v32, off offset:128
	v_or_b32_e32 v32, 32, v64
	v_ashrrev_i32_e32 v33, 31, v32
	v_lshlrev_b64 v[32:33], 12, v[32:33]
	v_add_f32_e32 v16, v142, v16
	v_lshl_add_u64 v[32:33], v[66:67], 0, v[32:33]
	global_store_dword v[32:33], v16, off
	v_or_b32_e32 v16, 33, v64
	v_add_f32_e32 v34, v140, v17
	v_ashrrev_i32_e32 v17, 31, v16
	v_lshlrev_b64 v[16:17], 12, v[16:17]
	v_lshl_add_u64 v[16:17], v[66:67], 0, v[16:17]
	global_store_dword v[16:17], v34, off
	v_or_b32_e32 v34, 34, v64
	v_ashrrev_i32_e32 v35, 31, v34
	v_lshlrev_b64 v[34:35], 12, v[34:35]
	v_add_f32_e32 v18, v138, v18
	v_lshl_add_u64 v[34:35], v[66:67], 0, v[34:35]
	global_store_dword v[34:35], v18, off
	v_or_b32_e32 v18, 35, v64
	v_add_f32_e32 v36, v134, v19
	v_ashrrev_i32_e32 v19, 31, v18
	v_lshlrev_b64 v[18:19], 12, v[18:19]
	v_lshl_add_u64 v[18:19], v[66:67], 0, v[18:19]
	global_store_dword v[18:19], v36, off
	v_or_b32_e32 v36, 40, v64
	v_ashrrev_i32_e32 v37, 31, v36
	v_lshlrev_b64 v[36:37], 12, v[36:37]
	v_add_f32_e32 v20, v135, v20
	v_lshl_add_u64 v[36:37], v[66:67], 0, v[36:37]
	global_store_dword v[36:37], v20, off
	v_or_b32_e32 v20, 41, v64
	v_add_f32_e32 v38, v132, v21
	v_ashrrev_i32_e32 v21, 31, v20
	v_lshlrev_b64 v[20:21], 12, v[20:21]
	v_lshl_add_u64 v[20:21], v[66:67], 0, v[20:21]
	global_store_dword v[20:21], v38, off
	v_or_b32_e32 v38, 42, v64
	v_ashrrev_i32_e32 v39, 31, v38
	v_lshlrev_b64 v[38:39], 12, v[38:39]
	v_add_f32_e32 v22, v126, v22
	v_lshl_add_u64 v[38:39], v[66:67], 0, v[38:39]
	global_store_dword v[38:39], v22, off
	v_or_b32_e32 v22, 43, v64
	v_add_f32_e32 v40, v122, v23
	v_ashrrev_i32_e32 v23, 31, v22
	v_lshlrev_b64 v[22:23], 12, v[22:23]
	v_lshl_add_u64 v[22:23], v[66:67], 0, v[22:23]
	global_store_dword v[22:23], v40, off
	v_or_b32_e32 v40, 48, v64
	v_ashrrev_i32_e32 v41, 31, v40
	v_lshlrev_b64 v[40:41], 12, v[40:41]
	v_add_f32_e32 v24, v123, v24
	v_lshl_add_u64 v[40:41], v[66:67], 0, v[40:41]
	global_store_dword v[40:41], v24, off
	v_or_b32_e32 v24, 49, v64
	v_add_f32_e32 v42, v120, v25
	v_ashrrev_i32_e32 v25, 31, v24
	v_lshlrev_b64 v[24:25], 12, v[24:25]
	v_lshl_add_u64 v[24:25], v[66:67], 0, v[24:25]
	global_store_dword v[24:25], v42, off
	v_or_b32_e32 v42, 50, v64
	v_ashrrev_i32_e32 v43, 31, v42
	v_lshlrev_b64 v[42:43], 12, v[42:43]
	v_add_f32_e32 v26, v118, v26
	v_lshl_add_u64 v[42:43], v[66:67], 0, v[42:43]
	global_store_dword v[42:43], v26, off
	v_or_b32_e32 v26, 51, v64
	v_add_f32_e32 v44, v114, v27
	v_ashrrev_i32_e32 v27, 31, v26
	v_lshlrev_b64 v[26:27], 12, v[26:27]
	v_lshl_add_u64 v[26:27], v[66:67], 0, v[26:27]
	global_store_dword v[26:27], v44, off
	v_or_b32_e32 v44, 56, v64
	v_add_f32_e32 v0, v85, v0
	v_ashrrev_i32_e32 v45, 31, v44
	global_store_dword v[32:33], v0, off offset:128
	v_add_f32_e32 v0, v80, v1
	v_lshlrev_b64 v[44:45], 12, v[44:45]
	global_store_dword v[16:17], v0, off offset:128
	v_add_f32_e32 v0, v77, v2
	v_add_f32_e32 v28, v115, v28
	v_lshl_add_u64 v[44:45], v[66:67], 0, v[44:45]
	global_store_dword v[34:35], v0, off offset:128
	v_add_f32_e32 v0, v76, v3
	global_store_dword v[44:45], v28, off
	v_or_b32_e32 v28, 57, v64
	global_store_dword v[18:19], v0, off offset:128
	v_add_f32_e32 v0, v92, v4
	v_add_f32_e32 v46, v112, v29
	v_ashrrev_i32_e32 v29, 31, v28
	global_store_dword v[36:37], v0, off offset:128
	v_add_f32_e32 v0, v86, v5
	v_lshlrev_b64 v[28:29], 12, v[28:29]
	global_store_dword v[20:21], v0, off offset:128
	v_add_f32_e32 v0, v81, v6
	v_lshl_add_u64 v[28:29], v[66:67], 0, v[28:29]
	global_store_dword v[38:39], v0, off offset:128
	v_add_f32_e32 v0, v78, v7
	global_store_dword v[28:29], v46, off
	v_or_b32_e32 v46, 58, v64
	global_store_dword v[22:23], v0, off offset:128
	v_add_f32_e32 v0, v99, v8
	v_ashrrev_i32_e32 v47, 31, v46
	global_store_dword v[40:41], v0, off offset:128
	v_add_f32_e32 v0, v93, v9
	v_lshlrev_b64 v[46:47], 12, v[46:47]
	global_store_dword v[24:25], v0, off offset:128
	v_add_f32_e32 v0, v87, v10
	v_add_f32_e32 v30, v110, v30
	v_lshl_add_u64 v[46:47], v[66:67], 0, v[46:47]
	global_store_dword v[42:43], v0, off offset:128
	v_add_f32_e32 v0, v82, v11
	global_store_dword v[46:47], v30, off
	v_or_b32_e32 v30, 59, v64
	global_store_dword v[26:27], v0, off offset:128
	v_add_f32_e32 v0, v104, v12
	v_add_f32_e32 v48, v108, v31
	v_ashrrev_i32_e32 v31, 31, v30
	global_store_dword v[44:45], v0, off offset:128
	v_add_f32_e32 v0, v100, v13
	s_xor_b64 s[54:55], s[54:55], -1
	v_lshlrev_b64 v[30:31], 12, v[30:31]
	global_store_dword v[28:29], v0, off offset:128
	v_add_f32_e32 v0, v94, v14
	v_lshl_add_u64 v[30:31], v[66:67], 0, v[30:31]
	global_store_dword v[46:47], v0, off offset:128
	v_add_f32_e32 v0, v88, v15
	s_and_b64 vcc, exec, s[54:55]
	s_mov_b32 s30, 0x3a800000
	global_store_dword v[62:63], v65, off
	global_store_dword v[30:31], v48, off
	global_store_dword v[30:31], v0, off offset:128
	s_cbranch_vccnz .LBB0_92
